# attention steady steps: the 32 exps spread two per PV MFMA over all sixteen instead of four after each of the first eight
# speedup vs baseline: 1.0076x; 1.0076x over previous
.LBB0_974:
	s_waitcnt lgkmcnt(14)
	v_mfma_f32_32x32x16_bf16 v[50:65], v[158:161], v[210:213], v[50:65]
	v_exp_f32_e32 v130, v130
	v_exp_f32_e32 v131, v131
	s_waitcnt lgkmcnt(12)
	v_mfma_f32_32x32x16_bf16 v[34:49], v[158:161], v[206:209], v[34:49]
	v_exp_f32_e32 v132, v132
	v_exp_f32_e32 v133, v133
	v_add_u32_e32 v94, s44, v241
	ds_read_b128 v[82:85], v94
	ds_read_b128 v[198:201], v94 offset:512
	s_waitcnt lgkmcnt(12)
	v_mfma_f32_32x32x16_bf16 v[50:65], v[154:157], v[98:101], v[50:65]
	v_exp_f32_e32 v134, v134
	v_exp_f32_e32 v135, v135
	ds_read_b128 v[202:205], v94 offset:2048
	ds_read_b128 v[194:197], v94 offset:2560
	s_waitcnt lgkmcnt(12)
	v_mfma_f32_32x32x16_bf16 v[34:49], v[154:157], v[102:105], v[34:49]
	v_exp_f32_e32 v136, v136
	v_exp_f32_e32 v137, v137
	ds_read_b128 v[190:193], v94 offset:4096
	ds_read_b128 v[186:189], v94 offset:4608
	s_waitcnt lgkmcnt(12)
	v_mfma_f32_32x32x16_bf16 v[50:65], v[150:153], v[106:109], v[50:65]
	v_exp_f32_e32 v138, v138
	v_exp_f32_e32 v139, v139
	ds_read_b128 v[182:185], v94 offset:6144
	ds_read_b128 v[178:181], v94 offset:6656
	s_waitcnt lgkmcnt(12)
	v_mfma_f32_32x32x16_bf16 v[34:49], v[150:153], v[110:113], v[34:49]
	v_exp_f32_e32 v140, v140
	v_exp_f32_e32 v141, v141
	s_waitcnt lgkmcnt(10)
	v_mfma_f32_32x32x16_bf16 v[50:65], v[146:149], v[86:89], v[50:65]
	v_exp_f32_e32 v142, v142
	v_exp_f32_e32 v143, v143
	s_waitcnt lgkmcnt(8)
	v_mfma_f32_32x32x16_bf16 v[34:49], v[146:149], v[90:93], v[34:49]
	v_exp_f32_e32 v144, v144
	v_exp_f32_e32 v145, v145
	v_add_u32_e32 v102, s40, v228
	ds_read_b64_tr_b16 v[86:87],v102 offset:0
	ds_read_b64_tr_b16 v[88:89],v102 offset:512
	ds_read_b64_tr_b16 v[90:91],v102 offset:1024
	ds_read_b64_tr_b16 v[92:93],v102 offset:1536
	ds_read_b64_tr_b16 v[94:95],v102 offset:2048
	ds_read_b64_tr_b16 v[96:97],v102 offset:2560
	ds_read_b64_tr_b16 v[98:99],v102 offset:3072
	ds_read_b64_tr_b16 v[100:101],v102 offset:3584
	s_waitcnt lgkmcnt(0)
	s_nop 0
	v_mfma_f32_32x32x16_bf16 v[18:33], v[158:161], v[86:89], v[18:33]
	v_exp_f32_e32 v114, v114
	v_exp_f32_e32 v115, v115
	ds_read_b64_tr_b16 v[86:87],v102 offset:4096
	ds_read_b64_tr_b16 v[88:89],v102 offset:4608
	v_mfma_f32_32x32x16_bf16 v[18:33], v[154:157], v[90:93], v[18:33]
	v_exp_f32_e32 v116, v116
	v_exp_f32_e32 v117, v117
	ds_read_b64_tr_b16 v[90:91],v102 offset:5120
	ds_read_b64_tr_b16 v[92:93],v102 offset:5632
	v_mfma_f32_32x32x16_bf16 v[18:33], v[150:153], v[94:97], v[18:33]
	v_exp_f32_e32 v118, v118
	v_exp_f32_e32 v119, v119
	ds_read_b64_tr_b16 v[94:95],v102 offset:6144
	ds_read_b64_tr_b16 v[96:97],v102 offset:6656
	v_mfma_f32_32x32x16_bf16 v[18:33], v[146:149], v[98:101], v[18:33]
	v_exp_f32_e32 v120, v120
	v_exp_f32_e32 v121, v121
	ds_read_b64_tr_b16 v[98:99],v102 offset:7168
	ds_read_b64_tr_b16 v[100:101],v102 offset:7680
	s_waitcnt lgkmcnt(0)
	v_mfma_f32_32x32x16_bf16 v[2:17], v[158:161], v[86:89], v[2:17]
	v_exp_f32_e32 v122, v122
	v_exp_f32_e32 v123, v123
	s_waitcnt vmcnt(3) lgkmcnt(0)
	s_barrier
	s_andn2_b64 vcc, exec, s[2:3]
	v_add_u32_e32 v229, s94, v243
	v_mfma_f32_32x32x16_bf16 v[2:17], v[154:157], v[90:93], v[2:17]
	v_exp_f32_e32 v124, v124
	v_exp_f32_e32 v125, v125
	v_mfma_f32_32x32x16_bf16 v[2:17], v[150:153], v[94:97], v[2:17]
	v_exp_f32_e32 v126, v126
	v_exp_f32_e32 v127, v127
	v_mfma_f32_32x32x16_bf16 v[2:17], v[146:149], v[98:101], v[2:17]
	v_exp_f32_e32 v128, v128
	v_exp_f32_e32 v129, v129
	s_cbranch_vccnz .LBB0_976
	s_waitcnt lgkmcnt(0)
	ds_read_b128 v[86:89], v229 offset:96
	ds_read_b128 v[90:93], v229 offset:64
	ds_read_b128 v[94:97], v229 offset:32
	ds_read_b128 v[98:101], v229
	s_waitcnt lgkmcnt(3)
	v_pk_mul_f32 v[62:63], v[62:63], v[86:87]
	s_waitcnt lgkmcnt(2)
	v_pk_mul_f32 v[58:59], v[58:59], v[90:91]
	s_waitcnt lgkmcnt(1)
	v_pk_mul_f32 v[54:55], v[54:55], v[94:95]
	v_pk_mul_f32 v[64:65], v[64:65], v[88:89]
	v_pk_mul_f32 v[60:61], v[60:61], v[92:93]
	v_pk_mul_f32 v[56:57], v[56:57], v[96:97]
	s_waitcnt lgkmcnt(0)
	v_pk_mul_f32 v[52:53], v[52:53], v[100:101]
	v_pk_mul_f32 v[50:51], v[50:51], v[98:99]
	v_pk_mul_f32 v[46:47], v[46:47], v[86:87]
	v_pk_mul_f32 v[42:43], v[42:43], v[90:91]
	v_pk_mul_f32 v[38:39], v[38:39], v[94:95]
	v_pk_mul_f32 v[48:49], v[48:49], v[88:89]
	v_pk_mul_f32 v[44:45], v[44:45], v[92:93]
	v_pk_mul_f32 v[40:41], v[40:41], v[96:97]
	v_pk_mul_f32 v[36:37], v[36:37], v[100:101]
	v_pk_mul_f32 v[34:35], v[34:35], v[98:99]
	v_pk_mul_f32 v[30:31], v[30:31], v[86:87]
	v_pk_mul_f32 v[26:27], v[26:27], v[90:91]
	v_pk_mul_f32 v[22:23], v[22:23], v[94:95]
	v_pk_mul_f32 v[32:33], v[32:33], v[88:89]
	v_pk_mul_f32 v[28:29], v[28:29], v[92:93]
	v_pk_mul_f32 v[24:25], v[24:25], v[96:97]
	v_pk_mul_f32 v[20:21], v[20:21], v[100:101]
	v_pk_mul_f32 v[18:19], v[18:19], v[98:99]
	v_pk_mul_f32 v[14:15], v[14:15], v[86:87]
	v_pk_mul_f32 v[10:11], v[10:11], v[90:91]
	v_pk_mul_f32 v[6:7], v[6:7], v[94:95]
	v_pk_mul_f32 v[16:17], v[16:17], v[88:89]
	v_pk_mul_f32 v[12:13], v[12:13], v[92:93]
	v_pk_mul_f32 v[8:9], v[8:9], v[96:97]
	v_pk_mul_f32 v[4:5], v[4:5], v[100:101]
	v_pk_mul_f32 v[2:3], v[2:3], v[98:99]

.LBB0_977:
	s_waitcnt lgkmcnt(14)
	v_mfma_f32_32x32x16_bf16 v[50:65], v[158:161], v[210:213], v[50:65]
	v_exp_f32_e32 v98, v98
	v_exp_f32_e32 v99, v99
	s_waitcnt lgkmcnt(12)
	v_mfma_f32_32x32x16_bf16 v[34:49], v[158:161], v[206:209], v[34:49]
	v_exp_f32_e32 v100, v100
	v_exp_f32_e32 v101, v101
	v_add_u32_e32 v126, s40, v241
	ds_read_b128 v[206:209], v126
	ds_read_b128 v[202:205], v126 offset:512
	s_waitcnt lgkmcnt(12)
	v_mfma_f32_32x32x16_bf16 v[50:65], v[154:157], v[130:133], v[50:65]
	v_exp_f32_e32 v102, v102
	v_exp_f32_e32 v103, v103
	ds_read_b128 v[198:201], v126 offset:2048
	ds_read_b128 v[194:197], v126 offset:2560
	s_waitcnt lgkmcnt(12)
	v_mfma_f32_32x32x16_bf16 v[34:49], v[154:157], v[134:137], v[34:49]
	v_exp_f32_e32 v104, v104
	v_exp_f32_e32 v105, v105
	ds_read_b128 v[190:193], v126 offset:4096
	ds_read_b128 v[186:189], v126 offset:4608
	s_waitcnt lgkmcnt(12)
	v_mfma_f32_32x32x16_bf16 v[50:65], v[150:153], v[138:141], v[50:65]
	v_exp_f32_e32 v106, v106
	v_exp_f32_e32 v107, v107
	ds_read_b128 v[182:185], v126 offset:6144
	ds_read_b128 v[178:181], v126 offset:6656
	s_waitcnt lgkmcnt(12)
	v_mfma_f32_32x32x16_bf16 v[34:49], v[150:153], v[114:117], v[34:49]
	v_exp_f32_e32 v108, v108
	v_exp_f32_e32 v109, v109
	s_waitcnt lgkmcnt(10)
	v_mfma_f32_32x32x16_bf16 v[50:65], v[146:149], v[118:121], v[50:65]
	v_exp_f32_e32 v110, v110
	v_exp_f32_e32 v111, v111
	s_waitcnt lgkmcnt(8)
	v_mfma_f32_32x32x16_bf16 v[34:49], v[146:149], v[122:125], v[34:49]
	v_exp_f32_e32 v112, v112
	v_exp_f32_e32 v113, v113
	v_add_u32_e32 v130, s45, v228
	ds_read_b64_tr_b16 v[114:115],v130 offset:0
	ds_read_b64_tr_b16 v[116:117],v130 offset:512
	ds_read_b64_tr_b16 v[118:119],v130 offset:1024
	ds_read_b64_tr_b16 v[120:121],v130 offset:1536
	ds_read_b64_tr_b16 v[122:123],v130 offset:2048
	ds_read_b64_tr_b16 v[124:125],v130 offset:2560
	ds_read_b64_tr_b16 v[126:127],v130 offset:3072
	ds_read_b64_tr_b16 v[128:129],v130 offset:3584
	s_waitcnt lgkmcnt(0)
	s_nop 0
	v_mfma_f32_32x32x16_bf16 v[18:33], v[158:161], v[114:117], v[18:33]
	v_exp_f32_e32 v82, v82
	v_exp_f32_e32 v83, v83
	ds_read_b64_tr_b16 v[114:115],v130 offset:4096
	ds_read_b64_tr_b16 v[116:117],v130 offset:4608
	v_mfma_f32_32x32x16_bf16 v[18:33], v[154:157], v[118:121], v[18:33]
	v_exp_f32_e32 v84, v84
	v_exp_f32_e32 v85, v85
	ds_read_b64_tr_b16 v[118:119],v130 offset:5120
	ds_read_b64_tr_b16 v[120:121],v130 offset:5632
	v_mfma_f32_32x32x16_bf16 v[18:33], v[150:153], v[122:125], v[18:33]
	v_exp_f32_e32 v86, v86
	v_exp_f32_e32 v87, v87
	ds_read_b64_tr_b16 v[122:123],v130 offset:6144
	ds_read_b64_tr_b16 v[124:125],v130 offset:6656
	v_mfma_f32_32x32x16_bf16 v[18:33], v[146:149], v[126:129], v[18:33]
	v_exp_f32_e32 v88, v88
	v_exp_f32_e32 v89, v89
	ds_read_b64_tr_b16 v[126:127],v130 offset:7168
	ds_read_b64_tr_b16 v[128:129],v130 offset:7680
	s_waitcnt lgkmcnt(0)
	v_mfma_f32_32x32x16_bf16 v[2:17], v[158:161], v[114:117], v[2:17]
	v_exp_f32_e32 v90, v90
	v_exp_f32_e32 v91, v91
	s_waitcnt vmcnt(3) lgkmcnt(0)
	s_barrier
	s_andn2_b64 vcc, exec, s[2:3]
	v_mfma_f32_32x32x16_bf16 v[2:17], v[154:157], v[118:121], v[2:17]
	v_exp_f32_e32 v92, v92
	v_exp_f32_e32 v93, v93
	v_mfma_f32_32x32x16_bf16 v[2:17], v[150:153], v[122:125], v[2:17]
	v_exp_f32_e32 v94, v94
	v_exp_f32_e32 v95, v95
	v_mfma_f32_32x32x16_bf16 v[2:17], v[146:149], v[126:129], v[2:17]
	v_exp_f32_e32 v96, v96
	v_exp_f32_e32 v97, v97
	s_cbranch_vccnz .LBB0_979
	s_waitcnt lgkmcnt(0)
	ds_read_b128 v[114:117], v229 offset:96
	ds_read_b128 v[118:121], v229 offset:64
	ds_read_b128 v[122:125], v229 offset:32
	ds_read_b128 v[126:129], v229
	s_waitcnt lgkmcnt(3)
	v_pk_mul_f32 v[62:63], v[62:63], v[114:115]
	s_waitcnt lgkmcnt(2)
	v_pk_mul_f32 v[58:59], v[58:59], v[118:119]
	s_waitcnt lgkmcnt(1)
	v_pk_mul_f32 v[54:55], v[54:55], v[122:123]
	v_pk_mul_f32 v[64:65], v[64:65], v[116:117]
	v_pk_mul_f32 v[60:61], v[60:61], v[120:121]
	v_pk_mul_f32 v[56:57], v[56:57], v[124:125]
	s_waitcnt lgkmcnt(0)
	v_pk_mul_f32 v[52:53], v[52:53], v[128:129]
	v_pk_mul_f32 v[50:51], v[50:51], v[126:127]
	v_pk_mul_f32 v[46:47], v[46:47], v[114:115]
	v_pk_mul_f32 v[42:43], v[42:43], v[118:119]
	v_pk_mul_f32 v[38:39], v[38:39], v[122:123]
	v_pk_mul_f32 v[48:49], v[48:49], v[116:117]
	v_pk_mul_f32 v[44:45], v[44:45], v[120:121]
	v_pk_mul_f32 v[40:41], v[40:41], v[124:125]
	v_pk_mul_f32 v[36:37], v[36:37], v[128:129]
	v_pk_mul_f32 v[34:35], v[34:35], v[126:127]
	v_pk_mul_f32 v[30:31], v[30:31], v[114:115]
	v_pk_mul_f32 v[26:27], v[26:27], v[118:119]
	v_pk_mul_f32 v[22:23], v[22:23], v[122:123]
	v_pk_mul_f32 v[32:33], v[32:33], v[116:117]
	v_pk_mul_f32 v[28:29], v[28:29], v[120:121]
	v_pk_mul_f32 v[24:25], v[24:25], v[124:125]
	v_pk_mul_f32 v[20:21], v[20:21], v[128:129]
	v_pk_mul_f32 v[18:19], v[18:19], v[126:127]
	v_pk_mul_f32 v[14:15], v[14:15], v[114:115]
	v_pk_mul_f32 v[10:11], v[10:11], v[118:119]
	v_pk_mul_f32 v[6:7], v[6:7], v[122:123]
	v_pk_mul_f32 v[16:17], v[16:17], v[116:117]
	v_pk_mul_f32 v[12:13], v[12:13], v[120:121]
	v_pk_mul_f32 v[8:9], v[8:9], v[124:125]
	v_pk_mul_f32 v[4:5], v[4:5], v[128:129]
	v_pk_mul_f32 v[2:3], v[2:3], v[126:127]

.LBB0_1080:
	s_waitcnt lgkmcnt(14)
	v_mfma_f32_32x32x16_bf16 v[50:65], v[166:169], v[210:213], v[50:65]
	v_exp_f32_e32 v130, v130
	v_exp_f32_e32 v131, v131
	s_waitcnt lgkmcnt(12)
	v_mfma_f32_32x32x16_bf16 v[34:49], v[166:169], v[206:209], v[34:49]
	v_exp_f32_e32 v132, v132
	v_exp_f32_e32 v133, v133
	v_add_u32_e32 v94, s43, v241
	ds_read_b128 v[82:85], v94
	ds_read_b128 v[198:201], v94 offset:512
	s_waitcnt lgkmcnt(12)
	v_mfma_f32_32x32x16_bf16 v[50:65], v[162:165], v[98:101], v[50:65]
	v_exp_f32_e32 v134, v134
	v_exp_f32_e32 v135, v135
	ds_read_b128 v[202:205], v94 offset:2048
	ds_read_b128 v[194:197], v94 offset:2560
	s_waitcnt lgkmcnt(12)
	v_mfma_f32_32x32x16_bf16 v[34:49], v[162:165], v[102:105], v[34:49]
	v_exp_f32_e32 v136, v136
	v_exp_f32_e32 v137, v137
	ds_read_b128 v[190:193], v94 offset:4096
	ds_read_b128 v[186:189], v94 offset:4608
	s_waitcnt lgkmcnt(12)
	v_mfma_f32_32x32x16_bf16 v[50:65], v[158:161], v[106:109], v[50:65]
	v_exp_f32_e32 v138, v138
	v_exp_f32_e32 v139, v139
	ds_read_b128 v[182:185], v94 offset:6144
	ds_read_b128 v[178:181], v94 offset:6656
	s_waitcnt lgkmcnt(12)
	v_mfma_f32_32x32x16_bf16 v[34:49], v[158:161], v[110:113], v[34:49]
	v_exp_f32_e32 v140, v140
	v_exp_f32_e32 v141, v141
	s_waitcnt lgkmcnt(10)
	v_mfma_f32_32x32x16_bf16 v[50:65], v[154:157], v[86:89], v[50:65]
	v_exp_f32_e32 v142, v142
	v_exp_f32_e32 v143, v143
	s_waitcnt lgkmcnt(8)
	v_mfma_f32_32x32x16_bf16 v[34:49], v[154:157], v[90:93], v[34:49]
	v_exp_f32_e32 v144, v144
	v_exp_f32_e32 v145, v145
	v_add_u32_e32 v102, s40, v228
	ds_read_b64_tr_b16 v[86:87],v102 offset:0
	ds_read_b64_tr_b16 v[88:89],v102 offset:512
	ds_read_b64_tr_b16 v[90:91],v102 offset:1024
	ds_read_b64_tr_b16 v[92:93],v102 offset:1536
	ds_read_b64_tr_b16 v[94:95],v102 offset:2048
	ds_read_b64_tr_b16 v[96:97],v102 offset:2560
	ds_read_b64_tr_b16 v[98:99],v102 offset:3072
	ds_read_b64_tr_b16 v[100:101],v102 offset:3584
	s_waitcnt lgkmcnt(0)
	s_nop 0
	v_mfma_f32_32x32x16_bf16 v[18:33], v[166:169], v[86:89], v[18:33]
	v_exp_f32_e32 v114, v114
	v_exp_f32_e32 v115, v115
	ds_read_b64_tr_b16 v[86:87],v102 offset:4096
	ds_read_b64_tr_b16 v[88:89],v102 offset:4608
	v_mfma_f32_32x32x16_bf16 v[18:33], v[162:165], v[90:93], v[18:33]
	v_exp_f32_e32 v116, v116
	v_exp_f32_e32 v117, v117
	ds_read_b64_tr_b16 v[90:91],v102 offset:5120
	ds_read_b64_tr_b16 v[92:93],v102 offset:5632
	v_mfma_f32_32x32x16_bf16 v[18:33], v[158:161], v[94:97], v[18:33]
	v_exp_f32_e32 v118, v118
	v_exp_f32_e32 v119, v119
	ds_read_b64_tr_b16 v[94:95],v102 offset:6144
	ds_read_b64_tr_b16 v[96:97],v102 offset:6656
	v_mfma_f32_32x32x16_bf16 v[18:33], v[154:157], v[98:101], v[18:33]
	v_exp_f32_e32 v120, v120
	v_exp_f32_e32 v121, v121
	ds_read_b64_tr_b16 v[98:99],v102 offset:7168
	ds_read_b64_tr_b16 v[100:101],v102 offset:7680
	s_waitcnt lgkmcnt(0)
	v_mfma_f32_32x32x16_bf16 v[2:17], v[166:169], v[86:89], v[2:17]
	v_exp_f32_e32 v122, v122
	v_exp_f32_e32 v123, v123
	s_waitcnt vmcnt(3) lgkmcnt(0)
	s_barrier
	s_andn2_b64 vcc, exec, s[2:3]
	v_add_u32_e32 v229, s39, v243
	v_mfma_f32_32x32x16_bf16 v[2:17], v[162:165], v[90:93], v[2:17]
	v_exp_f32_e32 v124, v124
	v_exp_f32_e32 v125, v125
	v_mfma_f32_32x32x16_bf16 v[2:17], v[158:161], v[94:97], v[2:17]
	v_exp_f32_e32 v126, v126
	v_exp_f32_e32 v127, v127
	v_mfma_f32_32x32x16_bf16 v[2:17], v[154:157], v[98:101], v[2:17]
	v_exp_f32_e32 v128, v128
	v_exp_f32_e32 v129, v129
	s_cbranch_vccnz .LBB0_1082
	s_waitcnt lgkmcnt(0)
	ds_read_b128 v[86:89], v229 offset:96
	ds_read_b128 v[90:93], v229 offset:64
	ds_read_b128 v[94:97], v229 offset:32
	ds_read_b128 v[98:101], v229
	s_waitcnt lgkmcnt(3)
	v_pk_mul_f32 v[62:63], v[62:63], v[86:87]
	s_waitcnt lgkmcnt(2)
	v_pk_mul_f32 v[58:59], v[58:59], v[90:91]
	s_waitcnt lgkmcnt(1)
	v_pk_mul_f32 v[54:55], v[54:55], v[94:95]
	v_pk_mul_f32 v[64:65], v[64:65], v[88:89]
	v_pk_mul_f32 v[60:61], v[60:61], v[92:93]
	v_pk_mul_f32 v[56:57], v[56:57], v[96:97]
	s_waitcnt lgkmcnt(0)
	v_pk_mul_f32 v[52:53], v[52:53], v[100:101]
	v_pk_mul_f32 v[50:51], v[50:51], v[98:99]
	v_pk_mul_f32 v[46:47], v[46:47], v[86:87]
	v_pk_mul_f32 v[42:43], v[42:43], v[90:91]
	v_pk_mul_f32 v[38:39], v[38:39], v[94:95]
	v_pk_mul_f32 v[48:49], v[48:49], v[88:89]
	v_pk_mul_f32 v[44:45], v[44:45], v[92:93]
	v_pk_mul_f32 v[40:41], v[40:41], v[96:97]
	v_pk_mul_f32 v[36:37], v[36:37], v[100:101]
	v_pk_mul_f32 v[34:35], v[34:35], v[98:99]
	v_pk_mul_f32 v[30:31], v[30:31], v[86:87]
	v_pk_mul_f32 v[26:27], v[26:27], v[90:91]
	v_pk_mul_f32 v[22:23], v[22:23], v[94:95]
	v_pk_mul_f32 v[32:33], v[32:33], v[88:89]
	v_pk_mul_f32 v[28:29], v[28:29], v[92:93]
	v_pk_mul_f32 v[24:25], v[24:25], v[96:97]
	v_pk_mul_f32 v[20:21], v[20:21], v[100:101]
	v_pk_mul_f32 v[18:19], v[18:19], v[98:99]
	v_pk_mul_f32 v[14:15], v[14:15], v[86:87]
	v_pk_mul_f32 v[10:11], v[10:11], v[90:91]
	v_pk_mul_f32 v[6:7], v[6:7], v[94:95]
	v_pk_mul_f32 v[16:17], v[16:17], v[88:89]
	v_pk_mul_f32 v[12:13], v[12:13], v[92:93]
	v_pk_mul_f32 v[8:9], v[8:9], v[96:97]
	v_pk_mul_f32 v[4:5], v[4:5], v[100:101]
	v_pk_mul_f32 v[2:3], v[2:3], v[98:99]

.LBB0_1083:
	s_waitcnt lgkmcnt(14)
	v_mfma_f32_32x32x16_bf16 v[50:65], v[166:169], v[210:213], v[50:65]
	v_exp_f32_e32 v98, v98
	v_exp_f32_e32 v99, v99
	s_waitcnt lgkmcnt(12)
	v_mfma_f32_32x32x16_bf16 v[34:49], v[166:169], v[206:209], v[34:49]
	v_exp_f32_e32 v100, v100
	v_exp_f32_e32 v101, v101
	v_add_u32_e32 v126, s40, v241
	ds_read_b128 v[206:209], v126
	ds_read_b128 v[198:201], v126 offset:512
	s_waitcnt lgkmcnt(12)
	v_mfma_f32_32x32x16_bf16 v[50:65], v[162:165], v[130:133], v[50:65]
	v_exp_f32_e32 v102, v102
	v_exp_f32_e32 v103, v103
	ds_read_b128 v[202:205], v126 offset:2048
	ds_read_b128 v[194:197], v126 offset:2560
	s_waitcnt lgkmcnt(12)
	v_mfma_f32_32x32x16_bf16 v[34:49], v[162:165], v[134:137], v[34:49]
	v_exp_f32_e32 v104, v104
	v_exp_f32_e32 v105, v105
	ds_read_b128 v[190:193], v126 offset:4096
	ds_read_b128 v[186:189], v126 offset:4608
	s_waitcnt lgkmcnt(12)
	v_mfma_f32_32x32x16_bf16 v[50:65], v[158:161], v[138:141], v[50:65]
	v_exp_f32_e32 v106, v106
	v_exp_f32_e32 v107, v107
	ds_read_b128 v[182:185], v126 offset:6144
	ds_read_b128 v[178:181], v126 offset:6656
	s_waitcnt lgkmcnt(12)
	v_mfma_f32_32x32x16_bf16 v[34:49], v[158:161], v[114:117], v[34:49]
	v_exp_f32_e32 v108, v108
	v_exp_f32_e32 v109, v109
	s_waitcnt lgkmcnt(10)
	v_mfma_f32_32x32x16_bf16 v[50:65], v[154:157], v[118:121], v[50:65]
	v_exp_f32_e32 v110, v110
	v_exp_f32_e32 v111, v111
	s_waitcnt lgkmcnt(8)
	v_mfma_f32_32x32x16_bf16 v[34:49], v[154:157], v[122:125], v[34:49]
	v_exp_f32_e32 v112, v112
	v_exp_f32_e32 v113, v113
	v_add_u32_e32 v130, s47, v228
	ds_read_b64_tr_b16 v[114:115],v130 offset:0
	ds_read_b64_tr_b16 v[116:117],v130 offset:512
	ds_read_b64_tr_b16 v[118:119],v130 offset:1024
	ds_read_b64_tr_b16 v[120:121],v130 offset:1536
	ds_read_b64_tr_b16 v[122:123],v130 offset:2048
	ds_read_b64_tr_b16 v[124:125],v130 offset:2560
	ds_read_b64_tr_b16 v[126:127],v130 offset:3072
	ds_read_b64_tr_b16 v[128:129],v130 offset:3584
	s_waitcnt lgkmcnt(0)
	s_nop 0
	v_mfma_f32_32x32x16_bf16 v[18:33], v[166:169], v[114:117], v[18:33]
	v_exp_f32_e32 v82, v82
	v_exp_f32_e32 v83, v83
	ds_read_b64_tr_b16 v[114:115],v130 offset:4096
	ds_read_b64_tr_b16 v[116:117],v130 offset:4608
	v_mfma_f32_32x32x16_bf16 v[18:33], v[162:165], v[118:121], v[18:33]
	v_exp_f32_e32 v84, v84
	v_exp_f32_e32 v85, v85
	ds_read_b64_tr_b16 v[118:119],v130 offset:5120
	ds_read_b64_tr_b16 v[120:121],v130 offset:5632
	v_mfma_f32_32x32x16_bf16 v[18:33], v[158:161], v[122:125], v[18:33]
	v_exp_f32_e32 v86, v86
	v_exp_f32_e32 v87, v87
	ds_read_b64_tr_b16 v[122:123],v130 offset:6144
	ds_read_b64_tr_b16 v[124:125],v130 offset:6656
	v_mfma_f32_32x32x16_bf16 v[18:33], v[154:157], v[126:129], v[18:33]
	v_exp_f32_e32 v88, v88
	v_exp_f32_e32 v89, v89
	ds_read_b64_tr_b16 v[126:127],v130 offset:7168
	ds_read_b64_tr_b16 v[128:129],v130 offset:7680
	s_waitcnt lgkmcnt(0)
	v_mfma_f32_32x32x16_bf16 v[2:17], v[166:169], v[114:117], v[2:17]
	v_exp_f32_e32 v90, v90
	v_exp_f32_e32 v91, v91
	s_waitcnt vmcnt(3) lgkmcnt(0)
	s_barrier
	s_andn2_b64 vcc, exec, s[2:3]
	v_mfma_f32_32x32x16_bf16 v[2:17], v[162:165], v[118:121], v[2:17]
	v_exp_f32_e32 v92, v92
	v_exp_f32_e32 v93, v93
	v_mfma_f32_32x32x16_bf16 v[2:17], v[158:161], v[122:125], v[2:17]
	v_exp_f32_e32 v94, v94
	v_exp_f32_e32 v95, v95
	v_mfma_f32_32x32x16_bf16 v[2:17], v[154:157], v[126:129], v[2:17]
	v_exp_f32_e32 v96, v96
	v_exp_f32_e32 v97, v97
	s_cbranch_vccnz .LBB0_1085
	s_waitcnt lgkmcnt(0)
	ds_read_b128 v[114:117], v229 offset:96
	ds_read_b128 v[118:121], v229 offset:64
	ds_read_b128 v[122:125], v229 offset:32
	ds_read_b128 v[126:129], v229
	s_waitcnt lgkmcnt(3)
	v_pk_mul_f32 v[62:63], v[62:63], v[114:115]
	s_waitcnt lgkmcnt(2)
	v_pk_mul_f32 v[58:59], v[58:59], v[118:119]
	s_waitcnt lgkmcnt(1)
	v_pk_mul_f32 v[54:55], v[54:55], v[122:123]
	v_pk_mul_f32 v[64:65], v[64:65], v[116:117]
	v_pk_mul_f32 v[60:61], v[60:61], v[120:121]
	v_pk_mul_f32 v[56:57], v[56:57], v[124:125]
	s_waitcnt lgkmcnt(0)
	v_pk_mul_f32 v[52:53], v[52:53], v[128:129]
	v_pk_mul_f32 v[50:51], v[50:51], v[126:127]
	v_pk_mul_f32 v[46:47], v[46:47], v[114:115]
	v_pk_mul_f32 v[42:43], v[42:43], v[118:119]
	v_pk_mul_f32 v[38:39], v[38:39], v[122:123]
	v_pk_mul_f32 v[48:49], v[48:49], v[116:117]
	v_pk_mul_f32 v[44:45], v[44:45], v[120:121]
	v_pk_mul_f32 v[40:41], v[40:41], v[124:125]
	v_pk_mul_f32 v[36:37], v[36:37], v[128:129]
	v_pk_mul_f32 v[34:35], v[34:35], v[126:127]
	v_pk_mul_f32 v[30:31], v[30:31], v[114:115]
	v_pk_mul_f32 v[26:27], v[26:27], v[118:119]
	v_pk_mul_f32 v[22:23], v[22:23], v[122:123]
	v_pk_mul_f32 v[32:33], v[32:33], v[116:117]
	v_pk_mul_f32 v[28:29], v[28:29], v[120:121]
	v_pk_mul_f32 v[24:25], v[24:25], v[124:125]
	v_pk_mul_f32 v[20:21], v[20:21], v[128:129]
	v_pk_mul_f32 v[18:19], v[18:19], v[126:127]
	v_pk_mul_f32 v[14:15], v[14:15], v[114:115]
	v_pk_mul_f32 v[10:11], v[10:11], v[118:119]
	v_pk_mul_f32 v[6:7], v[6:7], v[122:123]
	v_pk_mul_f32 v[16:17], v[16:17], v[116:117]
	v_pk_mul_f32 v[12:13], v[12:13], v[120:121]
	v_pk_mul_f32 v[8:9], v[8:9], v[124:125]
	v_pk_mul_f32 v[4:5], v[4:5], v[128:129]
	v_pk_mul_f32 v[2:3], v[2:3], v[126:127]
